# EpiConv: per-tile conv weights DMA'd to LDS at tile start, read by ds_read in the epilogue; removes the vmcnt(0) drain behind next-tile prefetch
# speedup vs baseline: 1.0402x; 1.0038x over previous
.LBB0_515:
	s_waitcnt lgkmcnt(3)
	v_mfma_f32_32x32x16_bf16 v[48:63], v[100:103], v[64:67], 0
	s_waitcnt lgkmcnt(2)
	v_mfma_f32_32x32x16_bf16 v[48:63], v[96:99], v[68:71], v[48:63]
	s_waitcnt lgkmcnt(1)
	v_mfma_f32_32x32x16_bf16 v[48:63], v[92:95], v[72:75], v[48:63]
	s_waitcnt lgkmcnt(0)
	v_mfma_f32_32x32x16_bf16 v[48:63], v[88:91], v[76:79], v[48:63]
	s_nop 2
	ds_read_b128 v[32:35], v131 offset:4608
	ds_read_b128 v[88:91], v131 offset:4640
	s_waitcnt lgkmcnt(1)
	v_mfma_f32_32x32x16_bf16 v[32:47], v[32:35], v[64:67], 0
	s_waitcnt lgkmcnt(0)
	v_mfma_f32_32x32x16_bf16 v[32:47], v[88:91], v[68:71], v[32:47]
	ds_read_b128 v[88:91], v131 offset:4672
	s_waitcnt lgkmcnt(0)
	v_mfma_f32_32x32x16_bf16 v[32:47], v[88:91], v[72:75], v[32:47]
	ds_read_b128 v[88:91], v131 offset:4704
	s_waitcnt lgkmcnt(0)
	v_mfma_f32_32x32x16_bf16 v[32:47], v[88:91], v[76:79], v[32:47]
	s_and_b64 vcc, s[66:67], s[0:1]
	v_cndmask_b32_e32 v48, v120, v48, vcc
	s_and_b64 vcc, s[66:67], s[10:11]
	v_cndmask_b32_e32 v49, v120, v49, vcc
	s_and_b64 vcc, s[66:67], s[2:3]
	v_cndmask_b32_e32 v50, v120, v50, vcc
	s_and_b64 vcc, s[66:67], s[4:5]
	v_cndmask_b32_e32 v51, v120, v51, vcc
	s_and_b64 vcc, s[66:67], s[6:7]
	v_cndmask_b32_e32 v52, v120, v52, vcc
	s_and_b64 vcc, s[66:67], s[8:9]
	v_cndmask_b32_e32 v53, v120, v53, vcc
	s_and_b64 vcc, s[66:67], s[14:15]
	v_cndmask_b32_e32 v54, v120, v54, vcc
	s_and_b64 vcc, s[66:67], s[16:17]
	v_cndmask_b32_e32 v55, v120, v55, vcc
	s_and_b64 vcc, s[66:67], s[18:19]
	v_cndmask_b32_e32 v56, v120, v56, vcc
	s_and_b64 vcc, s[66:67], s[20:21]
	v_cndmask_b32_e32 v57, v120, v57, vcc
	s_and_b64 vcc, s[66:67], s[22:23]
	v_cndmask_b32_e32 v58, v120, v58, vcc
	s_and_b64 vcc, s[66:67], s[24:25]
	v_cndmask_b32_e32 v59, v120, v59, vcc
	s_and_b64 vcc, s[66:67], s[26:27]
	v_cndmask_b32_e32 v60, v120, v60, vcc
	s_and_b64 vcc, s[66:67], s[28:29]
	v_cndmask_b32_e32 v61, v120, v61, vcc
	s_and_b64 vcc, s[66:67], s[30:31]
	v_cndmask_b32_e32 v62, v120, v62, vcc
	s_and_b64 vcc, s[66:67], s[34:35]
	v_cndmask_b32_e32 v63, v120, v63, vcc
	s_and_b64 vcc, s[66:67], s[36:37]
	v_cndmask_b32_e32 v32, v120, v32, vcc
	s_and_b64 vcc, s[66:67], s[12:13]
	v_max3_f32 v88, v48, s33, v49
	v_cndmask_b32_e32 v33, v120, v33, vcc
	s_and_b64 vcc, s[66:67], s[38:39]
	v_max3_f32 v88, v88, v50, v51
	v_cndmask_b32_e32 v34, v120, v34, vcc
	s_and_b64 vcc, s[66:67], s[40:41]
	v_max3_f32 v88, v88, v52, v53
	v_cndmask_b32_e32 v35, v120, v35, vcc
	s_and_b64 vcc, s[66:67], s[42:43]
	v_max3_f32 v88, v88, v54, v55
	v_cndmask_b32_e32 v36, v120, v36, vcc
	s_and_b64 vcc, s[66:67], s[44:45]
	v_max3_f32 v88, v88, v56, v57
	v_cndmask_b32_e32 v37, v120, v37, vcc
	s_and_b64 vcc, s[66:67], s[46:47]
	v_max3_f32 v88, v88, v58, v59
	v_cndmask_b32_e32 v38, v120, v38, vcc
	s_and_b64 vcc, s[66:67], s[48:49]
	v_max3_f32 v88, v88, v60, v61
	v_cndmask_b32_e32 v39, v120, v39, vcc
	s_and_b64 vcc, s[66:67], s[50:51]
	v_max3_f32 v88, v88, v62, v63
	v_cndmask_b32_e32 v40, v120, v40, vcc
	s_and_b64 vcc, s[66:67], s[52:53]
	v_max3_f32 v88, v88, v32, v33
	v_cndmask_b32_e32 v41, v120, v41, vcc
	s_and_b64 vcc, s[66:67], s[54:55]
	v_max3_f32 v88, v88, v34, v35
	v_cndmask_b32_e32 v42, v120, v42, vcc
	s_and_b64 vcc, s[66:67], s[56:57]
	v_max3_f32 v88, v88, v36, v37
	v_cndmask_b32_e32 v43, v120, v43, vcc
	s_and_b64 vcc, s[66:67], s[58:59]
	v_max3_f32 v88, v88, v38, v39
	v_cndmask_b32_e32 v44, v120, v44, vcc
	s_and_b64 vcc, s[66:67], s[60:61]
	v_max3_f32 v88, v88, v40, v41
	v_cndmask_b32_e32 v45, v120, v45, vcc
	s_and_b64 vcc, s[66:67], s[62:63]
	v_max3_f32 v88, v88, v42, v43
	v_cndmask_b32_e32 v46, v120, v46, vcc
	s_and_b64 vcc, s[66:67], s[64:65]
	v_max3_f32 v88, v88, v44, v45
	v_cndmask_b32_e32 v47, v120, v47, vcc
	v_max3_f32 v88, v88, v46, v47
	ds_bpermute_b32 v89, v113, v88
	s_waitcnt lgkmcnt(0)
	v_max3_f32 v128, v129, v88, v89
	v_sub_f32_e32 v48, v48, v128
	v_exp_f32_e32 v88, v48
	v_sub_f32_e32 v49, v49, v128
	v_exp_f32_e32 v90, v49
	v_sub_f32_e32 v49, v50, v128
	v_exp_f32_e32 v91, v49
	v_sub_f32_e32 v49, v51, v128
	v_exp_f32_e32 v92, v49
	v_sub_f32_e32 v49, v52, v128
	v_add_f32_e32 v89, 0, v88
	v_exp_f32_e32 v93, v49
	v_sub_f32_e32 v50, v53, v128
	v_add_f32_e32 v49, v90, v89
	v_exp_f32_e32 v89, v50
	v_sub_f32_e32 v50, v54, v128
	v_add_f32_e32 v49, v91, v49
	v_exp_f32_e32 v94, v50
	v_sub_f32_e32 v50, v55, v128
	v_add_f32_e32 v49, v92, v49
	v_exp_f32_e32 v95, v50
	v_sub_f32_e32 v50, v56, v128
	v_add_f32_e32 v49, v93, v49
	v_exp_f32_e32 v96, v50
	v_sub_f32_e32 v50, v57, v128
	v_add_f32_e32 v49, v89, v49
	v_exp_f32_e32 v97, v50
	v_sub_f32_e32 v50, v58, v128
	v_add_f32_e32 v49, v94, v49
	v_exp_f32_e32 v98, v50
	v_sub_f32_e32 v50, v59, v128
	v_add_f32_e32 v49, v95, v49
	v_exp_f32_e32 v99, v50
	v_sub_f32_e32 v50, v60, v128
	v_add_f32_e32 v49, v96, v49
	v_exp_f32_e32 v100, v50
	v_sub_f32_e32 v50, v61, v128
	v_add_f32_e32 v49, v97, v49
	v_exp_f32_e32 v101, v50
	v_sub_f32_e32 v50, v62, v128
	v_add_f32_e32 v49, v98, v49
	v_exp_f32_e32 v102, v50
	v_sub_f32_e32 v50, v63, v128
	v_add_f32_e32 v49, v99, v49
	v_exp_f32_e32 v103, v50
	v_sub_f32_e32 v32, v32, v128
	v_sub_f32_e32 v48, v129, v128
	v_add_f32_e32 v49, v100, v49
	v_exp_f32_e32 v129, v32
	v_sub_f32_e32 v33, v33, v128
	v_add_f32_e32 v32, v101, v49
	v_exp_f32_e32 v131, v33
	v_sub_f32_e32 v33, v34, v128
	v_add_f32_e32 v32, v102, v32
	v_exp_f32_e32 v132, v33
	v_sub_f32_e32 v33, v35, v128
	v_add_f32_e32 v32, v103, v32
	v_exp_f32_e32 v133, v33
	v_sub_f32_e32 v33, v36, v128
	v_add_f32_e32 v32, v129, v32
	v_exp_f32_e32 v134, v33
	v_sub_f32_e32 v33, v37, v128
	v_add_f32_e32 v32, v131, v32
	v_exp_f32_e32 v135, v33
	v_sub_f32_e32 v33, v38, v128
	v_add_f32_e32 v32, v132, v32
	v_exp_f32_e32 v136, v33
	v_sub_f32_e32 v33, v39, v128
	v_add_f32_e32 v32, v133, v32
	v_exp_f32_e32 v137, v33
	v_sub_f32_e32 v33, v40, v128
	v_add_f32_e32 v32, v134, v32
	v_exp_f32_e32 v138, v33
	v_sub_f32_e32 v33, v41, v128
	v_add_f32_e32 v32, v135, v32
	v_exp_f32_e32 v139, v33
	v_sub_f32_e32 v33, v42, v128
	v_add_f32_e32 v32, v136, v32
	v_exp_f32_e32 v140, v33
	v_sub_f32_e32 v33, v43, v128
	v_add_f32_e32 v32, v137, v32
	v_exp_f32_e32 v141, v33
	v_sub_f32_e32 v33, v44, v128
	v_add_f32_e32 v32, v138, v32
	v_exp_f32_e32 v142, v33
	v_add_f32_e32 v32, v139, v32
	v_add_f32_e32 v32, v140, v32
	v_add_f32_e32 v32, v141, v32
	v_add_f32_e32 v33, v142, v32
	v_sub_f32_e32 v32, v45, v128
	v_exp_f32_e32 v143, v32
	v_sub_f32_e32 v32, v46, v128
	v_exp_f32_e32 v144, v32
	v_sub_f32_e32 v32, v47, v128
	v_exp_f32_e32 v145, v32
	v_exp_f32_e32 v32, v48
	v_add_f32_e32 v33, v143, v33
	v_add_f32_e32 v33, v144, v33
	v_add_f32_e32 v130, v145, v33
	v_pk_mul_f32 v[38:39], v[6:7], v[32:33] op_sel_hi:[1,0]
	v_pk_mul_f32 v[36:37], v[4:5], v[32:33] op_sel_hi:[1,0]
	ds_read2_b64 v[4:7], v116 offset1:2
	v_fmac_f32_e32 v130, v117, v32
	v_pk_mul_f32 v[62:63], v[30:31], v[32:33] op_sel_hi:[1,0]
	v_pk_mul_f32 v[60:61], v[28:29], v[32:33] op_sel_hi:[1,0]
	v_pk_mul_f32 v[58:59], v[26:27], v[32:33] op_sel_hi:[1,0]
	v_pk_mul_f32 v[56:57], v[24:25], v[32:33] op_sel_hi:[1,0]
	v_pk_mul_f32 v[54:55], v[22:23], v[32:33] op_sel_hi:[1,0]
	v_pk_mul_f32 v[52:53], v[20:21], v[32:33] op_sel_hi:[1,0]
	v_pk_mul_f32 v[50:51], v[18:19], v[32:33] op_sel_hi:[1,0]
	v_pk_mul_f32 v[48:49], v[16:17], v[32:33] op_sel_hi:[1,0]
	v_pk_mul_f32 v[46:47], v[14:15], v[32:33] op_sel_hi:[1,0]
	v_pk_mul_f32 v[44:45], v[12:13], v[32:33] op_sel_hi:[1,0]
	v_pk_mul_f32 v[42:43], v[10:11], v[32:33] op_sel_hi:[1,0]
	v_pk_mul_f32 v[40:41], v[8:9], v[32:33] op_sel_hi:[1,0]
	v_pk_mul_f32 v[34:35], v[2:3], v[32:33] op_sel_hi:[1,0]
	v_pk_mul_f32 v[32:33], v[0:1], v[32:33] op_sel_hi:[1,0]
	v_cvt_pk_bf16_f32 v0, v88, v90
	v_cvt_pk_bf16_f32 v1, v91, v92
	v_cvt_pk_bf16_f32 v2, v93, v89
	v_cvt_pk_bf16_f32 v3, v94, v95
	ds_read2_b64 v[16:19], v116 offset0:4 offset1:6
	v_cvt_pk_bf16_f32 v8, v96, v97
	s_waitcnt lgkmcnt(1)
	v_mfma_f32_32x32x16_bf16 v[48:63], v[4:7], v[0:3], v[48:63]
	v_cvt_pk_bf16_f32 v9, v98, v99
	v_cvt_pk_bf16_f32 v10, v100, v101
	v_cvt_pk_bf16_f32 v11, v102, v103
	v_cvt_pk_bf16_f32 v12, v129, v131
	v_cvt_pk_bf16_f32 v13, v132, v133
	v_cvt_pk_bf16_f32 v14, v134, v135
	v_cvt_pk_bf16_f32 v15, v136, v137
	s_waitcnt lgkmcnt(0)
	v_mfma_f32_32x32x16_bf16 v[48:63], v[16:19], v[8:11], v[48:63]
	v_cvt_pk_bf16_f32 v4, v138, v139
	v_cvt_pk_bf16_f32 v5, v140, v141
	v_cvt_pk_bf16_f32 v6, v142, v143
	v_cvt_pk_bf16_f32 v7, v144, v145
	ds_read2_b64 v[16:19], v116 offset0:8 offset1:10
	s_waitcnt lgkmcnt(0)
	v_mfma_f32_32x32x16_bf16 v[48:63], v[16:19], v[12:15], v[48:63]
	ds_read2_b64 v[16:19], v116 offset0:12 offset1:14
	s_waitcnt lgkmcnt(0)
	v_mfma_f32_32x32x16_bf16 v[48:63], v[16:19], v[4:7], v[48:63]
	ds_read2_b64 v[16:19], v111 offset0:64 offset1:66
	s_waitcnt lgkmcnt(0)
	v_mfma_f32_32x32x16_bf16 v[32:47], v[16:19], v[0:3], v[32:47]
	ds_read2_b64 v[0:3], v111 offset0:68 offset1:70
	s_waitcnt lgkmcnt(0)
	v_mfma_f32_32x32x16_bf16 v[32:47], v[0:3], v[8:11], v[32:47]
	ds_read2_b64 v[0:3], v111 offset0:72 offset1:74
	s_waitcnt lgkmcnt(0)
	v_mfma_f32_32x32x16_bf16 v[32:47], v[0:3], v[12:15], v[32:47]
	ds_read2_b64 v[0:3], v111 offset0:76 offset1:78
	s_waitcnt lgkmcnt(0)
	v_mfma_f32_32x32x16_bf16 v[32:47], v[0:3], v[4:7], v[32:47]
	s_andn2_b64 vcc, exec, s[68:69]
	s_xor_b32 s73, s73, 1
	s_cbranch_vccz .LBB0_511
	s_branch .LBB0_512
	s_nop 0
	s_nop 0
	s_nop 0
	s_nop 0
	s_nop 0
	s_nop 0
	s_nop 0
	s_nop 0
	s_nop 0
	s_nop 0
	s_nop 0
	s_nop 0
	s_nop 0
	s_nop 0
	s_nop 0
	s_nop 0
	s_nop 0
	s_nop 0
	s_nop 0
	s_nop 0
	s_nop 0
	s_nop 0
	s_nop 0
	s_nop 0
	s_nop 0
	s_nop 0
	s_nop 0
	s_nop 0
	s_nop 0
	s_nop 0
	s_nop 0
	s_nop 0
	s_nop 0
	s_nop 0
	s_nop 0
	s_nop 0
	s_nop 0
	s_nop 0
	s_nop 0
	s_nop 0
	s_nop 0
	s_nop 0
	s_nop 0
	s_nop 0
	s_nop 0
	s_nop 0
	s_nop 0
	s_nop 0
	s_nop 0
	s_nop 0
	s_nop 0
	s_nop 0
	s_nop 0
	s_nop 0
	s_nop 0
	s_nop 0
	s_nop 0
	s_nop 0
	s_nop 0
	s_nop 0
	s_nop 0
	s_nop 0
	s_nop 0
	s_nop 0
	s_nop 0
	s_nop 0
	s_nop 0
	s_nop 0
	s_nop 0
	s_nop 0
	s_nop 0
	s_nop 0
	s_nop 0
	s_nop 0
	s_nop 0
	s_nop 0
	s_nop 0
	s_nop 0
	s_nop 0
	s_nop 0
	s_nop 0
	s_nop 0
	s_nop 0
	s_nop 0
	s_nop 0
	s_nop 0
	s_nop 0
	s_nop 0
	s_nop 0
	s_nop 0
	s_nop 0
	s_nop 0
	s_nop 0
	s_nop 0
	s_nop 0
	s_nop 0
	s_nop 0
	s_nop 0
	s_nop 0
	s_nop 0
	s_nop 0
	s_nop 0
	s_nop 0
	s_nop 0
	s_nop 0
	s_nop 0
	s_nop 0
	s_nop 0
	s_nop 0
	s_nop 0
	s_nop 0
	s_nop 0
	s_nop 0
	s_nop 0
	s_nop 0

.LBB0_704:
	v_readlane_b32 s98, v247, 1
	s_nop 1
	s_cmp_lg_u32 s98, 0
	s_cbranch_scc1 .Lwdma_skip
	v_mbcnt_lo_u32_b32 v180, -1, 0
	v_mbcnt_hi_u32_b32 v180, -1, v180
	v_and_b32_e32 v188, 31, v180
	v_lshlrev_b32_e32 v188, 4, v188
	s_lshl_b32 s99, s78, 9
	v_add_u32_e32 v188, s99, v188
	v_mov_b32_e32 v189, 0
	v_cmp_lt_u32_e64 s[100:101], 31, v180
	s_and_b32 s99, s67, 1
	s_lshl_b32 s99, s99, 12
	s_add_i32 s99, s99, 0x24000
	v_mov_b32_e32 v182, s0
	v_mov_b32_e32 v183, s1
	v_mov_b32_e32 v184, s28
	v_mov_b32_e32 v185, s29
	v_cndmask_b32_e64 v182, v182, v184, s[100:101]
	v_cndmask_b32_e64 v183, v183, v185, s[100:101]
	v_lshl_add_u64 v[182:183], v[182:183], 0, v[188:189]
	s_mov_b32 m0, s99
	s_nop 0
	global_load_lds_dwordx4 v[182:183], off
	v_mov_b32_e32 v182, s30
	v_mov_b32_e32 v183, s31
	v_mov_b32_e32 v184, s34
	v_mov_b32_e32 v185, s35
	v_cndmask_b32_e64 v182, v182, v184, s[100:101]
	v_cndmask_b32_e64 v183, v183, v185, s[100:101]
	v_lshl_add_u64 v[182:183], v[182:183], 0, v[188:189]
	s_add_i32 m0, s99, 0x400
	s_nop 0
	global_load_lds_dwordx4 v[182:183], off
	v_mov_b32_e32 v182, s36
	v_mov_b32_e32 v183, s37
	v_mov_b32_e32 v184, s38
	v_mov_b32_e32 v185, s39
	v_cndmask_b32_e64 v182, v182, v184, s[100:101]
	v_cndmask_b32_e64 v183, v183, v185, s[100:101]
	v_lshl_add_u64 v[182:183], v[182:183], 0, v[188:189]
	s_add_i32 m0, s99, 0x800
	s_nop 0
	global_load_lds_dwordx4 v[182:183], off
	v_mov_b32_e32 v182, s2
	v_mov_b32_e32 v183, s3
	v_mov_b32_e32 v184, s26
	v_mov_b32_e32 v185, s27
	v_cndmask_b32_e64 v182, v182, v184, s[100:101]
	v_cndmask_b32_e64 v183, v183, v185, s[100:101]
	v_lshl_add_u64 v[182:183], v[182:183], 0, v[188:189]
	s_add_i32 m0, s99, 0xc00
	s_nop 0
	global_load_lds_dwordx4 v[182:183], off

.LBB0_708:
	s_lshl_b32 s56, s78, 7
	v_add_u32_e32 v226, s56, v214
	v_ashrrev_i32_e32 v227, 31, v226
	s_and_b32 s98, s67, 1
	s_lshl_b32 s98, s98, 12
	s_add_i32 s98, s98, 0x24000
	v_lshl_add_u32 v64, v214, 2, s98
	ds_read_b128 v[68:71], v64 offset:16
	ds_read_b128 v[164:167], v64 offset:0
	s_nop 0
	ds_read_b128 v[48:51], v64 offset:528
	ds_read_b128 v[144:147], v64 offset:512
	ds_read_b128 v[72:75], v64 offset:1040
	ds_read_b128 v[168:171], v64 offset:1024
	s_nop 0
	ds_read_b128 v[52:55], v64 offset:1552
	ds_read_b128 v[148:151], v64 offset:1536
	s_waitcnt lgkmcnt(4)
	ds_read_b128 v[76:79], v64 offset:2064
	ds_read_b128 v[172:175], v64 offset:2048
	s_nop 0
	ds_read_b128 v[56:59], v64 offset:2576
	ds_read_b128 v[152:155], v64 offset:2560
	s_nop 0
	ds_read_b128 v[60:63], v64 offset:3088
	ds_read_b128 v[156:159], v64 offset:3072
	s_nop 0
	ds_read_b128 v[160:163], v64 offset:3584
	s_nop 0
	ds_read_b128 v[64:67], v64 offset:3600
	v_cndmask_b32_e64 v192, 0, 1, s[6:7]
	v_cmp_ne_u32_e64 s[10:11], 1, v192
	s_and_saveexec_b64 s[58:59], s[4:5]
	s_cbranch_execz .LBB0_711
	s_and_b64 vcc, exec, s[10:11]
	ds_write_b128 v228, v[136:139]
	ds_write_b128 v228, v[40:43] offset:16
	ds_write_b128 v228, v[128:131] offset:512
	ds_write_b128 v228, v[32:35] offset:528
	ds_write_b128 v229, v[104:107]
	ds_write_b128 v228, v[8:11] offset:4112
	ds_write_b128 v228, v[96:99] offset:4608
	ds_write_b128 v228, v[0:3] offset:4624
	s_cbranch_vccnz .LBB0_711
	s_ashr_i32 s55, s54, 31
	v_lshl_add_u64 v[192:193], s[54:55], 1, v[216:217]
	v_mov_b64_e32 v[194:195], s[16:17]
	v_mad_u64_u32 v[194:195], s[78:79], v192, s75, v[194:195]
	s_ashr_i32 s57, s56, 31
	v_mad_i32_i24 v195, v193, s75, v195
	v_lshl_add_u64 v[192:193], s[56:57], 1, v[194:195]
	v_lshlrev_b32_e32 v210, 1, v214
	v_lshl_add_u64 v[192:193], v[192:193], 0, v[210:211]
	v_cvt_pk_bf16_f32 v194, v104, v105
	global_store_dword v[192:193], v194, off
	v_cvt_pk_bf16_f32 v194, v106, v107
	global_store_dword v[192:193], v194, off offset:4
	v_cvt_pk_bf16_f32 v194, v8, v9
	global_store_dword v[192:193], v194, off offset:8
	v_cvt_pk_bf16_f32 v194, v10, v11
	global_store_dword v[192:193], v194, off offset:12
	v_lshl_add_u64 v[194:195], v[192:193], 0, s[40:41]
	v_add_co_u32_e32 v192, vcc, s76, v192
	v_cvt_pk_bf16_f32 v196, v96, v97
	s_nop 1
	v_addc_co_u32_e32 v193, vcc, 0, v193, vcc
	global_store_dword v[192:193], v196, off offset:1536
	v_cvt_pk_bf16_f32 v196, v98, v99
	global_store_dword v[194:195], v196, off offset:4
	v_cvt_pk_bf16_f32 v194, v0, v1
	global_store_dword v[192:193], v194, off offset:1544
	v_cvt_pk_bf16_f32 v194, v2, v3
	global_store_dword v[192:193], v194, off offset:1548

.LBB0_715:
	s_or_b64 exec, exec, s[56:57]
	s_waitcnt lgkmcnt(0)
	v_mov_b32_dpp v242, v198 row_ror:2 row_mask:0xf bank_mask:0xf
	v_mov_b32_dpp v193, v198 row_ror:1 row_mask:0xf bank_mask:0xf
	v_mov_b32_dpp v242, v188 row_shr:2 row_mask:0xf bank_mask:0xf
	v_mov_b32_dpp v193, v188 row_shr:1 row_mask:0xf bank_mask:0xf
	v_fma_f32 v242, v164, v242, v156
	v_fmac_f32_e32 v242, v168, v193
	v_fmac_f32_e32 v242, v188, v172
	v_mul_f32_e32 v193, 0xbfb8aa3b, v242
	v_exp_f32_e32 v193, v193
	v_mov_b32_dpp v243, v194 row_ror:2 row_mask:0xf bank_mask:0xf
	v_mov_b32_dpp v198, v194 row_ror:1 row_mask:0xf bank_mask:0xf
	v_lshl_add_u32 v210, s54, 8, v213
	v_add_f32_e32 v193, 1.0, v193
	v_rcp_f32_e32 v193, v193
	v_mov_b32_dpp v243, v184 row_shr:2 row_mask:0xf bank_mask:0xf
	v_mov_b32_dpp v198, v184 row_shr:1 row_mask:0xf bank_mask:0xf
	v_fma_f32 v194, v144, v243, v160
	v_fmac_f32_e32 v194, v148, v198
	v_fmac_f32_e32 v194, v184, v152
	v_mul_f32_e32 v193, v242, v193
	v_mul_f32_e32 v193, v194, v193
	v_mov_b32_dpp v198, v199 row_ror:2 row_mask:0xf bank_mask:0xf
	v_mov_b32_dpp v194, v199 row_ror:1 row_mask:0xf bank_mask:0xf
	v_mov_b32_dpp v198, v189 row_shr:2 row_mask:0xf bank_mask:0xf
	v_fma_f32 v198, v165, v198, v157
	v_mov_b32_dpp v194, v189 row_shr:1 row_mask:0xf bank_mask:0xf
	v_fmac_f32_e32 v198, v169, v194
	v_fmac_f32_e32 v198, v189, v173
	v_mul_f32_e32 v194, 0xbfb8aa3b, v198
	v_exp_f32_e32 v194, v194
	v_mov_b32_dpp v242, v195 row_ror:2 row_mask:0xf bank_mask:0xf
	v_add_f32_e32 v194, 1.0, v194
	v_rcp_f32_e32 v194, v194
	v_mov_b32_dpp v199, v195 row_ror:1 row_mask:0xf bank_mask:0xf
	v_mov_b32_dpp v242, v185 row_shr:2 row_mask:0xf bank_mask:0xf
	v_fma_f32 v195, v145, v242, v161
	v_mov_b32_dpp v199, v185 row_shr:1 row_mask:0xf bank_mask:0xf
	v_fmac_f32_e32 v195, v149, v199
	v_fmac_f32_e32 v195, v185, v153
	v_mul_f32_e32 v194, v198, v194
	v_mul_f32_e32 v242, v195, v194
	v_mov_b32_dpp v195, v200 row_ror:2 row_mask:0xf bank_mask:0xf
	v_mov_b32_dpp v194, v200 row_ror:1 row_mask:0xf bank_mask:0xf
	v_mov_b32_dpp v195, v190 row_shr:2 row_mask:0xf bank_mask:0xf
	v_mov_b32_dpp v194, v190 row_shr:1 row_mask:0xf bank_mask:0xf
	v_fma_f32 v195, v166, v195, v158
	v_fmac_f32_e32 v195, v170, v194
	v_fmac_f32_e32 v195, v190, v174
	v_mul_f32_e32 v194, 0xbfb8aa3b, v195
	v_exp_f32_e32 v194, v194
	v_mov_b32_dpp v199, v196 row_ror:2 row_mask:0xf bank_mask:0xf
	v_mov_b32_dpp v198, v196 row_ror:1 row_mask:0xf bank_mask:0xf
	v_cvt_pk_bf16_f32 v244, v193, v242
	v_add_f32_e32 v194, 1.0, v194
	v_rcp_f32_e32 v194, v194
	v_mov_b32_dpp v199, v186 row_shr:2 row_mask:0xf bank_mask:0xf
	v_mov_b32_dpp v198, v186 row_shr:1 row_mask:0xf bank_mask:0xf
	v_fma_f32 v196, v146, v199, v162
	v_fmac_f32_e32 v196, v150, v198
	v_fmac_f32_e32 v196, v186, v154
	v_mul_f32_e32 v194, v195, v194
	v_mul_f32_e32 v200, v196, v194
	v_mov_b32_dpp v195, v201 row_ror:2 row_mask:0xf bank_mask:0xf
	v_mov_b32_dpp v194, v201 row_ror:1 row_mask:0xf bank_mask:0xf
	v_mov_b32_dpp v195, v191 row_shr:2 row_mask:0xf bank_mask:0xf
	v_fma_f32 v195, v167, v195, v159
	v_mov_b32_dpp v194, v191 row_shr:1 row_mask:0xf bank_mask:0xf
	v_fmac_f32_e32 v195, v171, v194
	v_fmac_f32_e32 v195, v191, v175
	v_mul_f32_e32 v194, 0xbfb8aa3b, v195
	v_exp_f32_e32 v194, v194
	v_mov_b32_dpp v198, v197 row_ror:2 row_mask:0xf bank_mask:0xf
	v_add_f32_e32 v194, 1.0, v194
	v_rcp_f32_e32 v194, v194
	v_mov_b32_dpp v196, v197 row_ror:1 row_mask:0xf bank_mask:0xf
	v_mov_b32_dpp v198, v187 row_shr:2 row_mask:0xf bank_mask:0xf
	v_fma_f32 v197, v147, v198, v163
	v_mov_b32_dpp v196, v187 row_shr:1 row_mask:0xf bank_mask:0xf
	v_fmac_f32_e32 v197, v151, v196
	v_fmac_f32_e32 v197, v187, v155
	v_mul_f32_e32 v194, v195, v194
	v_mul_f32_e32 v201, v197, v194
	v_mov_b64_e32 v[194:195], s[12:13]
	v_mad_i64_i32 v[196:197], s[54:55], v210, s77, v[194:195]
	v_lshlrev_b64 v[198:199], 1, v[226:227]
	v_lshl_add_u64 v[196:197], v[196:197], 0, v[198:199]
	v_cvt_pk_bf16_f32 v245, v200, v201
	v_mov_b32_dpp v200, v188 row_ror:2 row_mask:0xf bank_mask:0xf
	v_mov_b32_dpp v193, v188 row_ror:1 row_mask:0xf bank_mask:0xf
	v_mov_b32_dpp v200, v180 row_shr:2 row_mask:0xf bank_mask:0xf
	v_fma_f32 v200, v164, v200, v156
	v_mov_b32_dpp v193, v180 row_shr:1 row_mask:0xf bank_mask:0xf
	v_fmac_f32_e32 v200, v168, v193
	v_fmac_f32_e32 v200, v180, v172
	v_mul_f32_e32 v193, 0xbfb8aa3b, v200
	v_exp_f32_e32 v193, v193
	v_mov_b32_dpp v201, v184 row_ror:2 row_mask:0xf bank_mask:0xf
	s_nop 0
	v_mov_b32_dpp v188, v184 row_ror:1 row_mask:0xf bank_mask:0xf
	v_add_f32_e32 v184, 1.0, v193
	v_rcp_f32_e32 v184, v184
	v_mov_b32_dpp v201, v176 row_shr:2 row_mask:0xf bank_mask:0xf
	v_mov_b32_dpp v188, v176 row_shr:1 row_mask:0xf bank_mask:0xf
	v_fma_f32 v193, v144, v201, v160
	v_fmac_f32_e32 v193, v148, v188
	v_fmac_f32_e32 v193, v176, v152
	v_mul_f32_e32 v184, v200, v184
	v_mul_f32_e32 v188, v193, v184
	v_mov_b32_dpp v193, v189 row_ror:2 row_mask:0xf bank_mask:0xf
	v_mov_b32_dpp v184, v189 row_ror:1 row_mask:0xf bank_mask:0xf
	v_mov_b32_dpp v193, v181 row_shr:2 row_mask:0xf bank_mask:0xf
	v_mov_b32_dpp v184, v181 row_shr:1 row_mask:0xf bank_mask:0xf
	v_fma_f32 v193, v165, v193, v157
	v_fmac_f32_e32 v193, v169, v184
	v_fmac_f32_e32 v193, v181, v173
	v_mul_f32_e32 v184, 0xbfb8aa3b, v193
	v_exp_f32_e32 v184, v184
	v_mov_b32_dpp v200, v185 row_ror:2 row_mask:0xf bank_mask:0xf
	v_mov_b32_dpp v189, v185 row_ror:1 row_mask:0xf bank_mask:0xf
	v_add_f32_e32 v184, 1.0, v184
	v_rcp_f32_e32 v184, v184
	v_mov_b32_dpp v200, v177 row_shr:2 row_mask:0xf bank_mask:0xf
	v_mov_b32_dpp v189, v177 row_shr:1 row_mask:0xf bank_mask:0xf
	v_fma_f32 v185, v145, v200, v161
	v_fmac_f32_e32 v185, v149, v189
	v_fmac_f32_e32 v185, v177, v153
	v_mul_f32_e32 v184, v193, v184
	v_mul_f32_e32 v189, v185, v184
	v_mov_b32_dpp v185, v190 row_ror:2 row_mask:0xf bank_mask:0xf
	v_mov_b32_dpp v184, v190 row_ror:1 row_mask:0xf bank_mask:0xf
	v_mov_b32_dpp v185, v182 row_shr:2 row_mask:0xf bank_mask:0xf
	v_mov_b32_dpp v184, v182 row_shr:1 row_mask:0xf bank_mask:0xf
	v_fma_f32 v185, v166, v185, v158
	v_fmac_f32_e32 v185, v170, v184
	v_fmac_f32_e32 v185, v182, v174
	v_mul_f32_e32 v184, 0xbfb8aa3b, v185
	v_exp_f32_e32 v184, v184
	v_mov_b32_dpp v193, v186 row_ror:2 row_mask:0xf bank_mask:0xf
	v_mov_b32_dpp v190, v186 row_ror:1 row_mask:0xf bank_mask:0xf
	v_cvt_pk_bf16_f32 v242, v188, v189
	v_add_f32_e32 v184, 1.0, v184
	v_rcp_f32_e32 v184, v184
	v_mov_b32_dpp v193, v178 row_shr:2 row_mask:0xf bank_mask:0xf
	v_mov_b32_dpp v190, v178 row_shr:1 row_mask:0xf bank_mask:0xf
	v_fma_f32 v186, v146, v193, v162
	v_fmac_f32_e32 v186, v150, v190
	v_fmac_f32_e32 v186, v178, v154
	v_mul_f32_e32 v184, v185, v184
	v_mul_f32_e32 v186, v186, v184
	v_mov_b32_dpp v185, v191 row_ror:2 row_mask:0xf bank_mask:0xf
	v_mov_b32_dpp v184, v191 row_ror:1 row_mask:0xf bank_mask:0xf
	v_mov_b32_dpp v185, v183 row_shr:2 row_mask:0xf bank_mask:0xf
	v_fma_f32 v185, v167, v185, v159
	v_mov_b32_dpp v184, v183 row_shr:1 row_mask:0xf bank_mask:0xf
	v_fmac_f32_e32 v185, v171, v184
	v_fmac_f32_e32 v185, v183, v175
	v_mul_f32_e32 v184, 0xbfb8aa3b, v185
	v_exp_f32_e32 v184, v184
	v_mov_b32_dpp v190, v187 row_ror:1 row_mask:0xf bank_mask:0xf
	v_mov_b32_e32 v193, 0
	v_add_f32_e32 v184, 1.0, v184
	v_mov_b32_dpp v191, v187 row_ror:2 row_mask:0xf bank_mask:0xf
	v_rcp_f32_e32 v184, v184
	v_mov_b32_dpp v190, v179 row_shr:1 row_mask:0xf bank_mask:0xf
	v_mov_b32_dpp v191, v179 row_shr:2 row_mask:0xf bank_mask:0xf
	v_fma_f32 v187, v147, v191, v163
	v_fmac_f32_e32 v187, v151, v190
	v_fmac_f32_e32 v187, v179, v155
	v_mul_f32_e32 v184, v185, v184
	v_mul_f32_e32 v187, v187, v184
	v_or_b32_e32 v184, 16, v210
	v_mad_i64_i32 v[184:185], s[54:55], v184, s77, v[194:195]
	v_lshl_add_u64 v[184:185], v[184:185], 0, v[198:199]
	v_cvt_pk_bf16_f32 v243, v186, v187
	v_mov_b32_dpp v187, v180 row_ror:2 row_mask:0xf bank_mask:0xf
	v_mov_b32_dpp v186, v180 row_ror:1 row_mask:0xf bank_mask:0xf
	v_mov_b32_dpp v187, v140 row_shr:2 row_mask:0xf bank_mask:0xf
	v_fma_f32 v187, v164, v187, v156
	v_mov_b32_dpp v186, v140 row_shr:1 row_mask:0xf bank_mask:0xf
	v_fmac_f32_e32 v187, v168, v186
	v_fmac_f32_e32 v187, v140, v172
	v_mul_f32_e32 v186, 0xbfb8aa3b, v187
	v_exp_f32_e32 v186, v186
	v_mov_b32_dpp v188, v176 row_ror:2 row_mask:0xf bank_mask:0xf
	s_nop 0
	v_mov_b32_dpp v180, v176 row_ror:1 row_mask:0xf bank_mask:0xf
	v_add_f32_e32 v176, 1.0, v186
	v_rcp_f32_e32 v176, v176
	v_mov_b32_dpp v188, v132 row_shr:2 row_mask:0xf bank_mask:0xf
	v_mov_b32_dpp v180, v132 row_shr:1 row_mask:0xf bank_mask:0xf
	v_fma_f32 v186, v144, v188, v160
	v_fmac_f32_e32 v186, v148, v180
	v_fmac_f32_e32 v186, v132, v152
	v_mul_f32_e32 v176, v187, v176
	v_mul_f32_e32 v180, v186, v176
	v_mov_b32_dpp v186, v181 row_ror:2 row_mask:0xf bank_mask:0xf
	v_mov_b32_dpp v176, v181 row_ror:1 row_mask:0xf bank_mask:0xf
	v_mov_b32_dpp v186, v141 row_shr:2 row_mask:0xf bank_mask:0xf
	v_mov_b32_dpp v176, v141 row_shr:1 row_mask:0xf bank_mask:0xf
	v_fma_f32 v186, v165, v186, v157
	v_fmac_f32_e32 v186, v169, v176
	v_fmac_f32_e32 v186, v141, v173
	v_mul_f32_e32 v176, 0xbfb8aa3b, v186
	v_exp_f32_e32 v176, v176
	v_mov_b32_dpp v187, v177 row_ror:2 row_mask:0xf bank_mask:0xf
	v_mov_b32_dpp v181, v177 row_ror:1 row_mask:0xf bank_mask:0xf
	v_add_f32_e32 v176, 1.0, v176
	v_rcp_f32_e32 v176, v176
	v_mov_b32_dpp v187, v133 row_shr:2 row_mask:0xf bank_mask:0xf
	v_mov_b32_dpp v181, v133 row_shr:1 row_mask:0xf bank_mask:0xf
	v_fma_f32 v177, v145, v187, v161
	v_fmac_f32_e32 v177, v149, v181
	v_fmac_f32_e32 v177, v133, v153
	v_mul_f32_e32 v176, v186, v176
	v_mul_f32_e32 v181, v177, v176
	v_mov_b32_dpp v177, v182 row_ror:2 row_mask:0xf bank_mask:0xf
	v_mov_b32_dpp v176, v182 row_ror:1 row_mask:0xf bank_mask:0xf
	v_mov_b32_dpp v177, v142 row_shr:2 row_mask:0xf bank_mask:0xf
	v_mov_b32_dpp v176, v142 row_shr:1 row_mask:0xf bank_mask:0xf
	v_fma_f32 v177, v166, v177, v158
	v_fmac_f32_e32 v177, v170, v176
	v_fmac_f32_e32 v177, v142, v174
	v_mul_f32_e32 v176, 0xbfb8aa3b, v177
	v_exp_f32_e32 v176, v176
	v_mov_b32_dpp v186, v178 row_ror:2 row_mask:0xf bank_mask:0xf
	v_mov_b32_dpp v182, v178 row_ror:1 row_mask:0xf bank_mask:0xf
	v_cvt_pk_bf16_f32 v200, v180, v181
	v_add_f32_e32 v176, 1.0, v176
	v_rcp_f32_e32 v176, v176
	v_mov_b32_dpp v186, v134 row_shr:2 row_mask:0xf bank_mask:0xf
	v_mov_b32_dpp v182, v134 row_shr:1 row_mask:0xf bank_mask:0xf
	v_fma_f32 v178, v146, v186, v162
	v_fmac_f32_e32 v178, v150, v182
	v_fmac_f32_e32 v178, v134, v154
	v_mul_f32_e32 v176, v177, v176
	v_mul_f32_e32 v178, v178, v176
	v_mov_b32_dpp v177, v183 row_ror:2 row_mask:0xf bank_mask:0xf
	v_mov_b32_dpp v176, v183 row_ror:1 row_mask:0xf bank_mask:0xf
	v_mov_b32_dpp v177, v143 row_shr:2 row_mask:0xf bank_mask:0xf
	v_fma_f32 v177, v167, v177, v159
	v_mov_b32_dpp v176, v143 row_shr:1 row_mask:0xf bank_mask:0xf
	v_fmac_f32_e32 v177, v171, v176
	v_fmac_f32_e32 v177, v143, v175
	v_mul_f32_e32 v176, 0xbfb8aa3b, v177
	v_exp_f32_e32 v176, v176
	v_mov_b32_dpp v182, v179 row_ror:1 row_mask:0xf bank_mask:0xf
	v_add_f32_e32 v176, 1.0, v176
	v_mov_b32_dpp v183, v179 row_ror:2 row_mask:0xf bank_mask:0xf
	v_rcp_f32_e32 v176, v176
	v_mov_b32_dpp v182, v135 row_shr:1 row_mask:0xf bank_mask:0xf
	v_mov_b32_dpp v183, v135 row_shr:2 row_mask:0xf bank_mask:0xf
	v_fma_f32 v179, v147, v183, v163
	v_fmac_f32_e32 v179, v151, v182
	v_fmac_f32_e32 v179, v135, v155
	v_mul_f32_e32 v176, v177, v176
	v_mul_f32_e32 v179, v179, v176
	v_or_b32_e32 v176, 32, v210
	v_mad_i64_i32 v[176:177], s[54:55], v176, s77, v[194:195]
	v_lshl_add_u64 v[176:177], v[176:177], 0, v[198:199]
	v_cvt_pk_bf16_f32 v201, v178, v179
	v_mov_b32_dpp v179, v140 row_ror:2 row_mask:0xf bank_mask:0xf
	s_nop 0
	v_mov_b32_dpp v178, v140 row_ror:1 row_mask:0xf bank_mask:0xf
	v_mov_b32_dpp v179, v136 row_shr:2 row_mask:0xf bank_mask:0xf
	v_fma_f32 v179, v164, v179, v156
	v_mov_b32_dpp v178, v136 row_shr:1 row_mask:0xf bank_mask:0xf
	v_fmac_f32_e32 v179, v168, v178
	v_fmac_f32_e32 v179, v136, v172
	v_mul_f32_e32 v136, 0xbfb8aa3b, v179
	v_exp_f32_e32 v136, v136
	s_nop 0
	v_mov_b32_dpp v140, v132 row_ror:1 row_mask:0xf bank_mask:0xf
	v_mov_b32_dpp v178, v132 row_ror:2 row_mask:0xf bank_mask:0xf
	v_add_f32_e32 v132, 1.0, v136
	v_rcp_f32_e32 v132, v132
	v_mov_b32_dpp v178, v128 row_shr:2 row_mask:0xf bank_mask:0xf
	v_mov_b32_dpp v140, v128 row_shr:1 row_mask:0xf bank_mask:0xf
	v_fma_f32 v136, v144, v178, v160
	v_fmac_f32_e32 v136, v148, v140
	v_fmac_f32_e32 v136, v128, v152
	v_mul_f32_e32 v128, v179, v132
	v_mul_f32_e32 v132, v136, v128
	v_mov_b32_dpp v136, v141 row_ror:2 row_mask:0xf bank_mask:0xf
	v_mov_b32_dpp v128, v141 row_ror:1 row_mask:0xf bank_mask:0xf
	v_mov_b32_dpp v140, v133 row_ror:1 row_mask:0xf bank_mask:0xf
	v_mov_b32_dpp v136, v137 row_shr:2 row_mask:0xf bank_mask:0xf
	v_mov_b32_dpp v128, v137 row_shr:1 row_mask:0xf bank_mask:0xf
	v_fma_f32 v136, v165, v136, v157
	v_fmac_f32_e32 v136, v169, v128
	v_fmac_f32_e32 v136, v137, v173
	v_mul_f32_e32 v128, 0xbfb8aa3b, v136
	v_exp_f32_e32 v128, v128
	v_mov_b32_dpp v140, v129 row_shr:1 row_mask:0xf bank_mask:0xf
	v_add_f32_e32 v128, 1.0, v128
	v_mov_b32_dpp v137, v133 row_ror:2 row_mask:0xf bank_mask:0xf
	v_rcp_f32_e32 v128, v128
	s_nop 0
	v_mov_b32_dpp v137, v129 row_shr:2 row_mask:0xf bank_mask:0xf
	v_fma_f32 v133, v145, v137, v161
	v_fmac_f32_e32 v133, v149, v140
	v_fmac_f32_e32 v133, v129, v153
	v_mul_f32_e32 v128, v136, v128
	v_mul_f32_e32 v133, v133, v128
	v_mov_b32_dpp v129, v142 row_ror:2 row_mask:0xf bank_mask:0xf
	v_mov_b32_dpp v128, v142 row_ror:1 row_mask:0xf bank_mask:0xf
	v_mov_b32_dpp v129, v138 row_shr:2 row_mask:0xf bank_mask:0xf
	v_fma_f32 v129, v166, v129, v158
	v_mov_b32_dpp v128, v138 row_shr:1 row_mask:0xf bank_mask:0xf
	v_fmac_f32_e32 v129, v170, v128
	v_fmac_f32_e32 v129, v138, v174
	v_mul_f32_e32 v128, 0xbfb8aa3b, v129
	v_exp_f32_e32 v128, v128
	v_mov_b32_dpp v137, v134 row_ror:2 row_mask:0xf bank_mask:0xf
	v_add_f32_e32 v128, 1.0, v128
	v_rcp_f32_e32 v128, v128
	v_mov_b32_dpp v136, v134 row_ror:1 row_mask:0xf bank_mask:0xf
	v_mov_b32_dpp v137, v130 row_shr:2 row_mask:0xf bank_mask:0xf
	v_fma_f32 v134, v146, v137, v162
	v_mov_b32_dpp v136, v130 row_shr:1 row_mask:0xf bank_mask:0xf
	v_fmac_f32_e32 v134, v150, v136
	v_fmac_f32_e32 v134, v130, v154
	v_mul_f32_e32 v128, v129, v128
	v_mul_f32_e32 v130, v134, v128
	v_mov_b32_dpp v129, v143 row_ror:2 row_mask:0xf bank_mask:0xf
	v_mov_b32_dpp v128, v143 row_ror:1 row_mask:0xf bank_mask:0xf
	v_mov_b32_dpp v129, v139 row_shr:2 row_mask:0xf bank_mask:0xf
	v_fma_f32 v129, v167, v129, v159
	v_mov_b32_dpp v128, v139 row_shr:1 row_mask:0xf bank_mask:0xf
	v_fmac_f32_e32 v129, v171, v128
	v_fmac_f32_e32 v129, v139, v175
	v_mul_f32_e32 v128, 0xbfb8aa3b, v129
	v_exp_f32_e32 v128, v128
	v_mov_b32_dpp v136, v135 row_ror:2 row_mask:0xf bank_mask:0xf
	v_add_f32_e32 v128, 1.0, v128
	v_rcp_f32_e32 v128, v128
	v_mov_b32_dpp v134, v135 row_ror:1 row_mask:0xf bank_mask:0xf
	v_mov_b32_dpp v136, v131 row_shr:2 row_mask:0xf bank_mask:0xf
	v_fma_f32 v135, v147, v136, v163
	v_mov_b32_dpp v134, v131 row_shr:1 row_mask:0xf bank_mask:0xf
	v_fmac_f32_e32 v135, v151, v134
	v_fmac_f32_e32 v135, v131, v155
	v_mul_f32_e32 v128, v129, v128
	v_mul_f32_e32 v131, v135, v128
	v_or_b32_e32 v128, 48, v210
	v_mad_i64_i32 v[128:129], s[54:55], v128, s77, v[194:195]
	v_lshl_add_u64 v[134:135], v[128:129], 0, v[198:199]
	v_cvt_pk_bf16_f32 v226, v132, v133
	v_cvt_pk_bf16_f32 v227, v130, v131
	v_mov_b32_e32 v194, 0
	v_mov_b32_e32 v195, 0
	v_mov_b32_e32 v130, 0
	v_mov_b32_e32 v131, 0
	v_mov_b32_e32 v132, 0
	v_mov_b32_e32 v133, 0
	s_and_saveexec_b64 s[54:55], s[4:5]
	s_cbranch_execz .LBB0_717
	ds_read_b128 v[192:195], v233
	ds_read_b128 v[130:133], v232

.LBB0_721:
	s_or_b64 exec, exec, s[54:55]
	s_waitcnt lgkmcnt(1)
	v_mov_b32_dpp v37, v128 row_ror:2 row_mask:0xf bank_mask:0xf
	v_mov_b32_dpp v36, v128 row_ror:1 row_mask:0xf bank_mask:0xf
	v_mov_b32_dpp v37, v28 row_shr:2 row_mask:0xf bank_mask:0xf
	v_mov_b32_dpp v36, v28 row_shr:1 row_mask:0xf bank_mask:0xf
	v_fma_f32 v37, v68, v37, v60
	v_fmac_f32_e32 v37, v72, v36
	v_fmac_f32_e32 v37, v28, v76
	v_mul_f32_e32 v36, 0xbfb8aa3b, v37
	v_exp_f32_e32 v36, v36
	s_waitcnt lgkmcnt(0)
	v_mov_b32_dpp v38, v32 row_ror:1 row_mask:0xf bank_mask:0xf
	v_mov_b32_dpp v39, v32 row_ror:2 row_mask:0xf bank_mask:0xf
	s_andn2_b64 vcc, exec, s[8:9]
	v_add_f32_e32 v32, 1.0, v36
	v_rcp_f32_e32 v32, v32
	v_mov_b32_dpp v39, v24 row_shr:2 row_mask:0xf bank_mask:0xf
	v_mov_b32_dpp v38, v24 row_shr:1 row_mask:0xf bank_mask:0xf
	v_fma_f32 v36, v48, v39, v64
	v_fmac_f32_e32 v36, v52, v38
	v_fmac_f32_e32 v36, v24, v56
	v_mul_f32_e32 v32, v37, v32
	v_mul_f32_e32 v32, v36, v32
	v_mov_b32_dpp v37, v129 row_ror:2 row_mask:0xf bank_mask:0xf
	v_mov_b32_dpp v36, v129 row_ror:1 row_mask:0xf bank_mask:0xf
	v_mov_b32_dpp v37, v29 row_shr:2 row_mask:0xf bank_mask:0xf
	v_fma_f32 v37, v69, v37, v61
	v_mov_b32_dpp v36, v29 row_shr:1 row_mask:0xf bank_mask:0xf
	v_fmac_f32_e32 v37, v73, v36
	v_fmac_f32_e32 v37, v29, v77
	v_mul_f32_e32 v36, 0xbfb8aa3b, v37
	v_exp_f32_e32 v36, v36
	v_mov_b32_dpp v38, v33 row_ror:1 row_mask:0xf bank_mask:0xf
	s_mov_b64 s[8:9], -1
	v_mov_b32_dpp v39, v33 row_ror:2 row_mask:0xf bank_mask:0xf
	v_add_f32_e32 v33, 1.0, v36
	v_rcp_f32_e32 v33, v33
	v_mov_b32_dpp v39, v25 row_shr:2 row_mask:0xf bank_mask:0xf
	v_mov_b32_dpp v38, v25 row_shr:1 row_mask:0xf bank_mask:0xf
	v_fma_f32 v36, v49, v39, v65
	v_fmac_f32_e32 v36, v53, v38
	v_fmac_f32_e32 v36, v25, v57
	v_mul_f32_e32 v33, v37, v33
	v_mul_f32_e32 v33, v36, v33
	v_mov_b32_dpp v37, v130 row_ror:2 row_mask:0xf bank_mask:0xf
	v_mov_b32_dpp v36, v130 row_ror:1 row_mask:0xf bank_mask:0xf
	v_mov_b32_dpp v37, v30 row_shr:2 row_mask:0xf bank_mask:0xf
	v_fma_f32 v37, v70, v37, v62
	v_mov_b32_dpp v36, v30 row_shr:1 row_mask:0xf bank_mask:0xf
	v_fmac_f32_e32 v37, v74, v36
	v_fmac_f32_e32 v37, v30, v78
	v_mul_f32_e32 v36, 0xbfb8aa3b, v37
	v_exp_f32_e32 v36, v36
	v_mov_b32_dpp v38, v34 row_ror:1 row_mask:0xf bank_mask:0xf
	v_cvt_pk_bf16_f32 v146, v32, v33
	v_mov_b32_dpp v39, v34 row_ror:2 row_mask:0xf bank_mask:0xf
	v_add_f32_e32 v34, 1.0, v36
	v_rcp_f32_e32 v34, v34
	v_mov_b32_dpp v39, v26 row_shr:2 row_mask:0xf bank_mask:0xf
	v_mov_b32_dpp v38, v26 row_shr:1 row_mask:0xf bank_mask:0xf
	v_fma_f32 v36, v50, v39, v66
	v_fmac_f32_e32 v36, v54, v38
	v_fmac_f32_e32 v36, v26, v58
	v_mul_f32_e32 v34, v37, v34
	v_mul_f32_e32 v34, v36, v34
	v_mov_b32_dpp v37, v131 row_ror:2 row_mask:0xf bank_mask:0xf
	v_mov_b32_dpp v36, v131 row_ror:1 row_mask:0xf bank_mask:0xf
	v_mov_b32_dpp v37, v31 row_shr:2 row_mask:0xf bank_mask:0xf
	v_fma_f32 v37, v71, v37, v63
	v_mov_b32_dpp v36, v31 row_shr:1 row_mask:0xf bank_mask:0xf
	v_fmac_f32_e32 v37, v75, v36
	v_fmac_f32_e32 v37, v31, v79
	v_mul_f32_e32 v36, 0xbfb8aa3b, v37
	v_exp_f32_e32 v36, v36
	v_mov_b32_dpp v38, v35 row_ror:1 row_mask:0xf bank_mask:0xf
	v_mov_b32_dpp v39, v35 row_ror:2 row_mask:0xf bank_mask:0xf
	v_add_f32_e32 v35, 1.0, v36
	v_rcp_f32_e32 v35, v35
	v_mov_b32_dpp v39, v27 row_shr:2 row_mask:0xf bank_mask:0xf
	v_mov_b32_dpp v38, v27 row_shr:1 row_mask:0xf bank_mask:0xf
	v_fma_f32 v36, v51, v39, v67
	v_fmac_f32_e32 v36, v55, v38
	v_fmac_f32_e32 v36, v27, v59
	v_mul_f32_e32 v35, v37, v35
	v_mul_f32_e32 v35, v36, v35
	v_cvt_pk_bf16_f32 v147, v34, v35
	v_mov_b32_e32 v144, v186
	v_mov_b32_e32 v145, v187
	global_store_dwordx4 v[132:133], v[144:147], off
	v_mov_b32_dpp v33, v28 row_ror:2 row_mask:0xf bank_mask:0xf
	v_mov_b32_dpp v32, v28 row_ror:1 row_mask:0xf bank_mask:0xf
	v_mov_b32_dpp v33, v20 row_shr:2 row_mask:0xf bank_mask:0xf
	v_fma_f32 v33, v68, v33, v60
	v_mov_b32_dpp v32, v20 row_shr:1 row_mask:0xf bank_mask:0xf
	v_fmac_f32_e32 v33, v72, v32
	v_fmac_f32_e32 v33, v20, v76
	v_mul_f32_e32 v32, 0xbfb8aa3b, v33
	v_exp_f32_e32 v32, v32
	v_mov_b32_dpp v34, v24 row_ror:2 row_mask:0xf bank_mask:0xf
	s_nop 0
	v_mov_b32_dpp v28, v24 row_ror:1 row_mask:0xf bank_mask:0xf
	v_add_f32_e32 v24, 1.0, v32
	v_rcp_f32_e32 v24, v24
	v_mov_b32_dpp v34, v16 row_shr:2 row_mask:0xf bank_mask:0xf
	v_mov_b32_dpp v28, v16 row_shr:1 row_mask:0xf bank_mask:0xf
	v_fma_f32 v32, v48, v34, v64
	v_fmac_f32_e32 v32, v52, v28
	v_fmac_f32_e32 v32, v16, v56
	v_mul_f32_e32 v24, v33, v24
	v_mul_f32_e32 v24, v32, v24
	v_mov_b32_dpp v32, v29 row_ror:2 row_mask:0xf bank_mask:0xf
	v_mov_b32_dpp v28, v29 row_ror:1 row_mask:0xf bank_mask:0xf
	v_mov_b32_dpp v32, v21 row_shr:2 row_mask:0xf bank_mask:0xf
	v_mov_b32_dpp v28, v21 row_shr:1 row_mask:0xf bank_mask:0xf
	v_fma_f32 v32, v69, v32, v61
	v_fmac_f32_e32 v32, v73, v28
	v_fmac_f32_e32 v32, v21, v77
	v_mul_f32_e32 v28, 0xbfb8aa3b, v32
	v_exp_f32_e32 v28, v28
	v_mov_b32_dpp v29, v25 row_ror:1 row_mask:0xf bank_mask:0xf
	v_mov_b32_dpp v33, v25 row_ror:2 row_mask:0xf bank_mask:0xf
	v_add_f32_e32 v25, 1.0, v28
	v_rcp_f32_e32 v25, v25
	v_mov_b32_dpp v33, v17 row_shr:2 row_mask:0xf bank_mask:0xf
	v_mov_b32_dpp v29, v17 row_shr:1 row_mask:0xf bank_mask:0xf
	v_fma_f32 v28, v49, v33, v65
	v_fmac_f32_e32 v28, v53, v29
	v_fmac_f32_e32 v28, v17, v57
	v_mul_f32_e32 v25, v32, v25
	v_mul_f32_e32 v25, v28, v25
	v_mov_b32_dpp v29, v30 row_ror:2 row_mask:0xf bank_mask:0xf
	v_mov_b32_dpp v28, v30 row_ror:1 row_mask:0xf bank_mask:0xf
	v_mov_b32_dpp v29, v22 row_shr:2 row_mask:0xf bank_mask:0xf
	v_fma_f32 v29, v70, v29, v62
	v_mov_b32_dpp v28, v22 row_shr:1 row_mask:0xf bank_mask:0xf
	v_fmac_f32_e32 v29, v74, v28
	v_fmac_f32_e32 v29, v22, v78
	v_mul_f32_e32 v28, 0xbfb8aa3b, v29
	v_exp_f32_e32 v28, v28
	v_mov_b32_dpp v32, v26 row_ror:2 row_mask:0xf bank_mask:0xf
	v_cvt_pk_bf16_f32 v146, v24, v25
	v_mov_b32_dpp v30, v26 row_ror:1 row_mask:0xf bank_mask:0xf
	v_add_f32_e32 v26, 1.0, v28
	v_rcp_f32_e32 v26, v26
	v_mov_b32_dpp v32, v18 row_shr:2 row_mask:0xf bank_mask:0xf
	v_mov_b32_dpp v30, v18 row_shr:1 row_mask:0xf bank_mask:0xf
	v_fma_f32 v28, v50, v32, v66
	v_fmac_f32_e32 v28, v54, v30
	v_fmac_f32_e32 v28, v18, v58
	v_mul_f32_e32 v26, v29, v26
	v_mul_f32_e32 v26, v28, v26
	v_mov_b32_dpp v29, v31 row_ror:2 row_mask:0xf bank_mask:0xf
	v_mov_b32_dpp v28, v31 row_ror:1 row_mask:0xf bank_mask:0xf
	v_mov_b32_dpp v29, v23 row_shr:2 row_mask:0xf bank_mask:0xf
	v_fma_f32 v29, v71, v29, v63
	v_mov_b32_dpp v28, v23 row_shr:1 row_mask:0xf bank_mask:0xf
	v_fmac_f32_e32 v29, v75, v28
	v_fmac_f32_e32 v29, v23, v79
	v_mul_f32_e32 v28, 0xbfb8aa3b, v29
	v_exp_f32_e32 v28, v28
	v_mov_b32_dpp v30, v27 row_ror:1 row_mask:0xf bank_mask:0xf
	v_mov_b32_dpp v31, v27 row_ror:2 row_mask:0xf bank_mask:0xf
	v_add_f32_e32 v27, 1.0, v28
	v_rcp_f32_e32 v27, v27
	v_mov_b32_dpp v31, v19 row_shr:2 row_mask:0xf bank_mask:0xf
	v_mov_b32_dpp v30, v19 row_shr:1 row_mask:0xf bank_mask:0xf
	v_fma_f32 v28, v51, v31, v67
	v_fmac_f32_e32 v28, v55, v30
	v_fmac_f32_e32 v28, v19, v59
	v_mul_f32_e32 v27, v29, v27
	v_mul_f32_e32 v27, v28, v27
	v_cvt_pk_bf16_f32 v147, v26, v27
	v_mov_b32_e32 v144, v188
	v_mov_b32_e32 v145, v189
	global_store_dwordx4 v[120:121], v[144:147], off
	v_mov_b32_dpp v25, v20 row_ror:2 row_mask:0xf bank_mask:0xf
	v_mov_b32_dpp v24, v20 row_ror:1 row_mask:0xf bank_mask:0xf
	v_mov_b32_dpp v25, v12 row_shr:2 row_mask:0xf bank_mask:0xf
	v_fma_f32 v25, v68, v25, v60
	v_mov_b32_dpp v24, v12 row_shr:1 row_mask:0xf bank_mask:0xf
	v_fmac_f32_e32 v25, v72, v24
	v_fmac_f32_e32 v25, v12, v76
	v_mul_f32_e32 v24, 0xbfb8aa3b, v25
	v_exp_f32_e32 v24, v24
	v_mov_b32_dpp v26, v16 row_ror:2 row_mask:0xf bank_mask:0xf
	s_nop 0
	v_mov_b32_dpp v20, v16 row_ror:1 row_mask:0xf bank_mask:0xf
	v_add_f32_e32 v16, 1.0, v24
	v_rcp_f32_e32 v16, v16
	v_mov_b32_dpp v26, v4 row_shr:2 row_mask:0xf bank_mask:0xf
	v_mov_b32_dpp v20, v4 row_shr:1 row_mask:0xf bank_mask:0xf
	v_fma_f32 v24, v48, v26, v64
	v_fmac_f32_e32 v24, v52, v20
	v_fmac_f32_e32 v24, v4, v56
	v_mul_f32_e32 v16, v25, v16
	v_mul_f32_e32 v16, v24, v16
	v_mov_b32_dpp v24, v21 row_ror:2 row_mask:0xf bank_mask:0xf
	v_mov_b32_dpp v20, v21 row_ror:1 row_mask:0xf bank_mask:0xf
	v_mov_b32_dpp v24, v13 row_shr:2 row_mask:0xf bank_mask:0xf
	v_mov_b32_dpp v20, v13 row_shr:1 row_mask:0xf bank_mask:0xf
	v_fma_f32 v24, v69, v24, v61
	v_fmac_f32_e32 v24, v73, v20
	v_fmac_f32_e32 v24, v13, v77
	v_mul_f32_e32 v20, 0xbfb8aa3b, v24
	v_exp_f32_e32 v20, v20
	v_mov_b32_dpp v21, v17 row_ror:1 row_mask:0xf bank_mask:0xf
	v_mov_b32_dpp v25, v17 row_ror:2 row_mask:0xf bank_mask:0xf
	v_add_f32_e32 v17, 1.0, v20
	v_rcp_f32_e32 v17, v17
	v_mov_b32_dpp v25, v5 row_shr:2 row_mask:0xf bank_mask:0xf
	v_mov_b32_dpp v21, v5 row_shr:1 row_mask:0xf bank_mask:0xf
	v_fma_f32 v20, v49, v25, v65
	v_fmac_f32_e32 v20, v53, v21
	v_fmac_f32_e32 v20, v5, v57
	v_mul_f32_e32 v17, v24, v17
	v_mul_f32_e32 v17, v20, v17
	v_mov_b32_dpp v21, v22 row_ror:2 row_mask:0xf bank_mask:0xf
	v_mov_b32_dpp v20, v22 row_ror:1 row_mask:0xf bank_mask:0xf
	v_mov_b32_dpp v21, v14 row_shr:2 row_mask:0xf bank_mask:0xf
	v_fma_f32 v21, v70, v21, v62
	v_mov_b32_dpp v20, v14 row_shr:1 row_mask:0xf bank_mask:0xf
	v_fmac_f32_e32 v21, v74, v20
	v_fmac_f32_e32 v21, v14, v78
	v_mul_f32_e32 v20, 0xbfb8aa3b, v21
	v_exp_f32_e32 v20, v20
	v_mov_b32_dpp v24, v18 row_ror:2 row_mask:0xf bank_mask:0xf
	v_cvt_pk_bf16_f32 v146, v16, v17
	v_mov_b32_dpp v22, v18 row_ror:1 row_mask:0xf bank_mask:0xf
	v_add_f32_e32 v18, 1.0, v20
	v_rcp_f32_e32 v18, v18
	v_mov_b32_dpp v24, v6 row_shr:2 row_mask:0xf bank_mask:0xf
	v_mov_b32_dpp v22, v6 row_shr:1 row_mask:0xf bank_mask:0xf
	v_fma_f32 v20, v50, v24, v66
	v_fmac_f32_e32 v20, v54, v22
	v_fmac_f32_e32 v20, v6, v58
	v_mul_f32_e32 v18, v21, v18
	v_mul_f32_e32 v18, v20, v18
	v_mov_b32_dpp v21, v23 row_ror:2 row_mask:0xf bank_mask:0xf
	v_mov_b32_dpp v20, v23 row_ror:1 row_mask:0xf bank_mask:0xf
	v_mov_b32_dpp v21, v15 row_shr:2 row_mask:0xf bank_mask:0xf
	v_fma_f32 v21, v71, v21, v63
	v_mov_b32_dpp v20, v15 row_shr:1 row_mask:0xf bank_mask:0xf
	v_fmac_f32_e32 v21, v75, v20
	v_fmac_f32_e32 v21, v15, v79
	v_mul_f32_e32 v20, 0xbfb8aa3b, v21
	v_exp_f32_e32 v20, v20
	v_mov_b32_dpp v22, v19 row_ror:1 row_mask:0xf bank_mask:0xf
	v_mov_b32_dpp v23, v19 row_ror:2 row_mask:0xf bank_mask:0xf
	v_add_f32_e32 v19, 1.0, v20
	v_rcp_f32_e32 v19, v19
	v_mov_b32_dpp v23, v7 row_shr:2 row_mask:0xf bank_mask:0xf
	v_mov_b32_dpp v22, v7 row_shr:1 row_mask:0xf bank_mask:0xf
	v_fma_f32 v20, v51, v23, v67
	v_fmac_f32_e32 v20, v55, v22
	v_fmac_f32_e32 v20, v7, v59
	v_mul_f32_e32 v19, v21, v19
	v_mul_f32_e32 v19, v20, v19
	v_cvt_pk_bf16_f32 v147, v18, v19
	v_mov_b32_e32 v144, v190
	v_mov_b32_e32 v145, v191
	global_store_dwordx4 v[112:113], v[144:147], off
	v_mov_b32_dpp v17, v12 row_ror:2 row_mask:0xf bank_mask:0xf
	s_nop 0
	v_mov_b32_dpp v16, v12 row_ror:1 row_mask:0xf bank_mask:0xf
	v_mov_b32_dpp v17, v8 row_shr:2 row_mask:0xf bank_mask:0xf
	v_fma_f32 v17, v68, v17, v60
	v_mov_b32_dpp v16, v8 row_shr:1 row_mask:0xf bank_mask:0xf
	v_fmac_f32_e32 v17, v72, v16
	v_fmac_f32_e32 v17, v8, v76
	v_mul_f32_e32 v8, 0xbfb8aa3b, v17
	v_exp_f32_e32 v8, v8
	s_nop 0
	v_mov_b32_dpp v12, v4 row_ror:1 row_mask:0xf bank_mask:0xf
	v_mov_b32_dpp v16, v4 row_ror:2 row_mask:0xf bank_mask:0xf
	v_add_f32_e32 v4, 1.0, v8
	v_rcp_f32_e32 v4, v4
	v_mov_b32_dpp v16, v0 row_shr:2 row_mask:0xf bank_mask:0xf
	v_mov_b32_dpp v12, v0 row_shr:1 row_mask:0xf bank_mask:0xf
	v_fma_f32 v8, v48, v16, v64
	v_fmac_f32_e32 v8, v52, v12
	v_fmac_f32_e32 v8, v0, v56
	v_mul_f32_e32 v0, v17, v4
	v_mul_f32_e32 v0, v8, v0
	v_mov_b32_dpp v8, v13 row_ror:2 row_mask:0xf bank_mask:0xf
	v_mov_b32_dpp v4, v13 row_ror:1 row_mask:0xf bank_mask:0xf
	v_mov_b32_dpp v12, v5 row_ror:1 row_mask:0xf bank_mask:0xf
	v_mov_b32_dpp v8, v9 row_shr:2 row_mask:0xf bank_mask:0xf
	v_mov_b32_dpp v4, v9 row_shr:1 row_mask:0xf bank_mask:0xf
	v_fma_f32 v8, v69, v8, v61
	v_fmac_f32_e32 v8, v73, v4
	v_fmac_f32_e32 v8, v9, v77
	v_mul_f32_e32 v4, 0xbfb8aa3b, v8
	v_exp_f32_e32 v4, v4
	v_mov_b32_dpp v12, v1 row_shr:1 row_mask:0xf bank_mask:0xf
	v_add_f32_e32 v4, 1.0, v4
	v_mov_b32_dpp v9, v5 row_ror:2 row_mask:0xf bank_mask:0xf
	v_rcp_f32_e32 v4, v4
	s_nop 0
	v_mov_b32_dpp v9, v1 row_shr:2 row_mask:0xf bank_mask:0xf
	v_fma_f32 v5, v49, v9, v65
	v_fmac_f32_e32 v5, v53, v12
	v_fmac_f32_e32 v5, v1, v57
	v_mul_f32_e32 v1, v8, v4
	v_mul_f32_e32 v1, v5, v1
	v_mov_b32_dpp v5, v14 row_ror:2 row_mask:0xf bank_mask:0xf
	v_mov_b32_dpp v4, v14 row_ror:1 row_mask:0xf bank_mask:0xf
	v_mov_b32_dpp v5, v10 row_shr:2 row_mask:0xf bank_mask:0xf
	v_mov_b32_dpp v4, v10 row_shr:1 row_mask:0xf bank_mask:0xf
	v_fma_f32 v5, v70, v5, v62
	v_fmac_f32_e32 v5, v74, v4
	v_fmac_f32_e32 v5, v10, v78
	v_mul_f32_e32 v4, 0xbfb8aa3b, v5
	v_exp_f32_e32 v4, v4
	v_mov_b32_dpp v9, v6 row_ror:2 row_mask:0xf bank_mask:0xf
	v_mov_b32_dpp v8, v6 row_ror:1 row_mask:0xf bank_mask:0xf
	v_cvt_pk_bf16_f32 v146, v0, v1
	v_add_f32_e32 v4, 1.0, v4
	v_rcp_f32_e32 v4, v4
	v_mov_b32_dpp v9, v2 row_shr:2 row_mask:0xf bank_mask:0xf
	v_mov_b32_dpp v8, v2 row_shr:1 row_mask:0xf bank_mask:0xf
	v_fma_f32 v6, v50, v9, v66
	v_fmac_f32_e32 v6, v54, v8
	v_fmac_f32_e32 v6, v2, v58
	v_mul_f32_e32 v2, v5, v4
	v_mul_f32_e32 v2, v6, v2
	v_mov_b32_dpp v5, v15 row_ror:2 row_mask:0xf bank_mask:0xf
	v_mov_b32_dpp v4, v15 row_ror:1 row_mask:0xf bank_mask:0xf
	v_mov_b32_dpp v5, v11 row_shr:2 row_mask:0xf bank_mask:0xf
	v_mov_b32_dpp v4, v11 row_shr:1 row_mask:0xf bank_mask:0xf
	v_fmac_f32_e32 v63, v71, v5
	v_fmac_f32_e32 v63, v75, v4
	v_fmac_f32_e32 v63, v11, v79
	v_mul_f32_e32 v4, 0xbfb8aa3b, v63
	v_exp_f32_e32 v4, v4
	v_mov_b32_dpp v6, v7 row_ror:1 row_mask:0xf bank_mask:0xf
	v_add_f32_e32 v4, 1.0, v4
	v_mov_b32_dpp v5, v7 row_ror:2 row_mask:0xf bank_mask:0xf
	v_rcp_f32_e32 v4, v4
	v_mov_b32_dpp v6, v3 row_shr:1 row_mask:0xf bank_mask:0xf
	v_mov_b32_dpp v5, v3 row_shr:2 row_mask:0xf bank_mask:0xf
	v_fmac_f32_e32 v67, v51, v5
	v_fmac_f32_e32 v67, v55, v6
	v_fmac_f32_e32 v67, v3, v59
	v_mul_f32_e32 v3, v63, v4
	v_mul_f32_e32 v3, v67, v3
	v_cvt_pk_bf16_f32 v147, v2, v3
	v_mov_b32_e32 v144, v192
	v_mov_b32_e32 v145, v193
	global_store_dwordx4 v[104:105], v[144:147], off
	s_cbranch_vccnz .LBB0_701
	s_and_b64 vcc, exec, s[10:11]
	s_cbranch_vccnz .LBB0_700
	s_barrier
	s_branch .LBB0_700
	s_nop 0
	s_nop 0
	s_nop 0
	s_nop 0
	s_nop 0
	s_nop 0
	s_nop 0
	s_nop 0
	s_nop 0
	s_nop 0
	s_nop 0
	s_nop 0
	s_nop 0
	s_nop 0
	s_nop 0
	s_nop 0
	s_nop 0
	s_nop 0
	s_nop 0
	s_nop 0
	s_nop 0
	s_nop 0
	s_nop 0
	s_nop 0
	s_nop 0
	s_nop 0
	s_nop 0
	s_nop 0
	s_nop 0
	s_nop 0
	s_nop 0
	s_nop 0
	s_nop 0
	s_nop 0
	s_nop 0
	s_nop 0
	s_nop 0
	s_nop 0
	s_nop 0
	s_nop 0
	s_nop 0
	s_nop 0
	s_nop 0
	s_nop 0
	s_nop 0
	s_nop 0
	s_nop 0
	s_nop 0
	s_nop 0
	s_nop 0
	s_nop 0
	s_nop 0
	s_nop 0
	s_nop 0
	s_nop 0
	s_nop 0
	s_nop 0
	s_nop 0
	s_nop 0
	s_nop 0
	s_nop 0
	s_nop 0
	s_nop 0
	s_nop 0
	s_nop 0
	s_nop 0
	s_nop 0
	s_nop 0
	s_nop 0
	s_nop 0
	s_nop 0
	s_nop 0
	s_nop 0
	s_nop 0
	s_nop 0
	s_nop 0
	s_nop 0
	s_nop 0
	s_nop 0
	s_nop 0
	s_nop 0
	s_nop 0
	s_nop 0
	s_nop 0
	s_nop 0
	s_nop 0
	s_nop 0
	s_nop 0
	s_nop 0
	s_nop 0
	s_nop 0
	s_nop 0
	s_nop 0
	s_nop 0
